# GEMM phase prologues: second batch of 6 LDS-DMA stage loads issued right behind the first 8 with one counted vmcnt(8) instead of after the first batch's wait+barrier (pipeline fill pays one latency, 7
# speedup vs baseline: 1.0004x; 1.0004x over previous
; #define PG8_STAGE(bufoff, gbase, voff) do { _Pragma("unroll") for (int _i = 0; _i < 2; ++_i) \
;         __builtin_amdgcn_global_load_lds((const unsigned*)((const char*)(gbase) + (voff)[_i]), (LAS unsigned*)(lds + (bufoff) + ldsw + _i * 8192), 16, 0, 0); } while (0)
; #define PG8_WAIT_V(n) asm volatile("s_waitcnt vmcnt(" #n ")" ::: "memory")
; #define PG8_BAR __builtin_amdgcn_s_barrier()
; template <class Epi>
; __device__ __forceinline__ void gemm_phase(LAS unsigned char* lds, const Gemm g, const StaticOrder& S, const Epi& E) {
;     ...
;     for (int i = 0; i < 2; ++i) { int R, C; stage_rc(tid * 16 + i * 8192, R, C); const int Rb = Epi::PERM ? ((R & ~31) + perm32(R & 31)) : R;
;         voffA[i] = (unsigned)(R * g.lda + C) * 2u; voffB[i] = (unsigned)(Rb * K + C) * 2u; }
;     const size_t kstep = (size_t)(BK * 2);
;     const size_t hstepA = (size_t)HALF * g.lda * 2, hstepB = (size_t)HALF * K * 2;
;     const size_t tstepA = 2 * hstepA, tstepB = 2 * hstepB;
;     const unsigned ldsw = (unsigned)wid * 1024u;
;     const int aoff = lds_byte(wr * 64 + fr, fq * 8), boff = lds_byte(wc * 32 + fr, fq * 8);
;     ...
;     PG8_STAGE(PG8_SB(0, 0), cB, voffB); PG8_STAGE(PG8_SB(0, 1), cB + hstepB, voffB); PG8_STAGE(PG8_SA(0, 0), cA, voffA); PG8_STAGE(PG8_SA(0, 1), cA + hstepA, voffA);
;     if (wr == 1) PG8_BAR;
;     PG8_WAIT_V(2); PG8_BAR;
;     PG8_STAGE(PG8_SB(1, 0), cB + kstep, voffB); PG8_STAGE(PG8_SA(1, 0), cA + kstep, voffA); PG8_STAGE(PG8_SB(1, 1), cB + hstepB + kstep, voffB);
;     PG8_WAIT_V(6); PG8_BAR;
.LBB0_126:
	s_and_b64 s[0:1], s[0:1], exec
	v_readlane_b32 s0, v255, 22
	v_readlane_b32 s16, v255, 30
	v_readlane_b32 s1, v255, 23
	v_readlane_b32 s17, v255, 31
	s_cselect_b32 s17, s17, s1
	s_cselect_b32 s16, s16, s0
	s_add_i32 m0, s71, 0x18000
	v_lshl_add_u64 v[0:1], v[0:1], 0, s[90:91]
	global_load_lds_dwordx4 v[0:1], off
	v_lshl_add_u64 v[0:1], v[2:3], 0, s[90:91]
	s_add_i32 m0, s71, 0x1a000
	s_add_i32 s77, s71, 0x8000
	global_load_lds_dwordx4 v[0:1], off
	v_lshl_add_u64 v[0:1], v[8:9], 0, s[90:91]
	s_mov_b32 m0, s77
	s_add_i32 s78, s71, 0xa000
	global_load_lds_dwordx4 v[0:1], off
	v_lshl_add_u64 v[0:1], v[10:11], 0, s[90:91]
	s_mov_b32 m0, s78
	v_lshrrev_b32_e32 v20, 1, v18
	global_load_lds_dwordx4 v[0:1], off
	s_add_i32 m0, s71, 0x1c000
	v_lshl_add_u64 v[0:1], v[4:5], 0, s[90:91]
	global_load_lds_dwordx4 v[0:1], off
	v_lshl_add_u64 v[0:1], v[6:7], 0, s[90:91]
	s_add_i32 m0, s71, 0x1e000
	v_and_b32_e32 v20, 24, v20
	global_load_lds_dwordx4 v[0:1], off
	s_waitcnt vmcnt(8)
	s_barrier
	v_and_b32_e32 v19, 15, v18
	v_lshlrev_b32_e32 v21, 1, v20
	v_lshlrev_b32_e32 v18, 2, v18
	v_lshl_or_b32 v21, v19, 6, v21
	s_lshl_b32 s0, s5, 13
	v_and_b32_e32 v18, 32, v18
	v_bitop3_b32 v22, v21, s0, v18 bitop3:0xde
	s_lshl_b32 s0, s18, 5
	v_lshlrev_b32_e32 v0, 10, v19
	v_readlane_b32 s36, v254, 43
	s_lshr_b32 s76, s19, 6
	s_and_b32 s0, s0, 0x60
	v_lshl_or_b32 v157, s5, 16, v0
	v_add_u32_e32 v0, v14, v12
	v_readlane_b32 s44, v254, 51
	v_readlane_b32 s45, v254, 52
	s_lshl_b32 s1, s0, 7
	s_waitcnt vmcnt(6)
	s_add_i32 s79, s76, -2
	v_add_lshl_u32 v32, v0, v13, 1
	s_mov_b64 s[20:21], s[44:45]
	v_add_u32_e32 v0, v17, v15
	s_cmpk_lt_u32 s4, 0x100
	v_lshl_add_u64 v[146:147], s[20:21], 0, v[32:33]
	v_add_lshl_u32 v32, v0, v16, 1
	v_bitop3_b32 v156, v21, s1, v18 bitop3:0xde
	s_cselect_b64 s[18:19], -1, 0
	v_or_b32_e32 v158, s0, v20
	v_lshl_add_u64 v[148:149], s[20:21], 0, v[32:33]
	s_mov_b32 s80, 0
	v_add_u32_e32 v159, 0, v22
	s_mov_b32 s89, s30
	s_mov_b32 s92, s29
	s_barrier
	v_readlane_b32 s37, v254, 44
	v_readlane_b32 s38, v254, 45
	v_readlane_b32 s39, v254, 46
	v_readlane_b32 s40, v254, 47
	v_readlane_b32 s41, v254, 48
	v_readlane_b32 s42, v254, 49
	v_readlane_b32 s43, v254, 50
	v_readlane_b32 s46, v254, 53
	v_readlane_b32 s47, v254, 54
	v_readlane_b32 s48, v254, 55
	v_readlane_b32 s49, v254, 56
	v_readlane_b32 s50, v254, 57
	v_readlane_b32 s51, v254, 58
	s_branch .LBB0_129

; #define PG8_STAGE(bufoff, gbase, voff) do { _Pragma("unroll") for (int _i = 0; _i < 2; ++_i) \
;         __builtin_amdgcn_global_load_lds((const unsigned*)((const char*)(gbase) + (voff)[_i]), (LAS unsigned*)(lds + (bufoff) + ldsw + _i * 8192), 16, 0, 0); } while (0)
; #define PG8_WAIT_V(n) asm volatile("s_waitcnt vmcnt(" #n ")" ::: "memory")
; #define PG8_BAR __builtin_amdgcn_s_barrier()
; template <class Epi>
; __device__ __forceinline__ void gemm_phase(LAS unsigned char* lds, const Gemm g, const StaticOrder& S, const Epi& E) {
;     ...
;     for (int i = 0; i < 2; ++i) { int R, C; stage_rc(tid * 16 + i * 8192, R, C); const int Rb = Epi::PERM ? ((R & ~31) + perm32(R & 31)) : R;
;         voffA[i] = (unsigned)(R * g.lda + C) * 2u; voffB[i] = (unsigned)(Rb * K + C) * 2u; }
;     const size_t kstep = (size_t)(BK * 2);
;     const size_t hstepA = (size_t)HALF * g.lda * 2, hstepB = (size_t)HALF * K * 2;
;     const size_t tstepA = 2 * hstepA, tstepB = 2 * hstepB;
;     const unsigned ldsw = (unsigned)wid * 1024u;
;     const int aoff = lds_byte(wr * 64 + fr, fq * 8), boff = lds_byte(wc * 32 + fr, fq * 8);
;     ...
;     PG8_STAGE(PG8_SB(0, 0), cB, voffB); PG8_STAGE(PG8_SB(0, 1), cB + hstepB, voffB); PG8_STAGE(PG8_SA(0, 0), cA, voffA); PG8_STAGE(PG8_SA(0, 1), cA + hstepA, voffA);
;     if (wr == 1) PG8_BAR;
;     PG8_WAIT_V(2); PG8_BAR;
;     PG8_STAGE(PG8_SB(1, 0), cB + kstep, voffB); PG8_STAGE(PG8_SA(1, 0), cA + kstep, voffA); PG8_STAGE(PG8_SB(1, 1), cB + hstepB + kstep, voffB);
;     PG8_WAIT_V(6); PG8_BAR;
.LBB0_204:
	v_bfe_u32 v16, v14, 4, 2
	v_and_b32_e32 v15, 15, v14
	v_lshlrev_b32_e32 v18, 4, v16
	v_lshlrev_b32_e32 v14, 2, v14
	s_and_b32 s10, s6, 3
	v_lshl_or_b32 v144, s5, 6, v15
	v_lshl_or_b32 v15, v15, 6, v18
	s_lshl_b32 s5, s5, 13
	v_and_b32_e32 v14, 32, v14
	s_add_i32 m0, s28, 0x18000
	v_lshl_add_u64 v[6:7], v[6:7], 0, s[90:91]
	s_and_b32 s69, 0xffff, s7
	v_bitop3_b32 v18, v15, s5, v14 bitop3:0xde
	s_lshl_b32 s5, s10, 12
	global_load_lds_dwordx4 v[6:7], off
	v_lshl_add_u64 v[4:5], v[4:5], 0, s[90:91]
	s_add_i32 m0, s28, 0x1a000
	s_add_i32 s35, s28, 0x8000
	s_add_i32 s54, s28, 0xa000
	global_load_lds_dwordx4 v[4:5], off
	v_lshl_add_u64 v[0:1], v[0:1], 0, s[90:91]
	s_mov_b32 m0, s35
	s_add_u32 s6, s18, 0x40080
	global_load_lds_dwordx4 v[0:1], off
	v_lshl_add_u64 v[0:1], v[2:3], 0, s[90:91]
	s_mov_b32 m0, s54
	s_addc_u32 s7, s19, 0
	global_load_lds_dwordx4 v[0:1], off
	s_add_i32 m0, s28, 0x1c000
	v_lshl_add_u64 v[0:1], s[6:7], 0, v[134:135]
	global_load_lds_dwordx4 v[0:1], off
	v_lshl_add_u64 v[0:1], s[6:7], 0, v[130:131]
	s_add_i32 m0, s28, 0x1e000
	s_cmpk_lt_u32 s4, 0x100
	global_load_lds_dwordx4 v[0:1], off
	s_waitcnt vmcnt(8)
	s_barrier
	v_lshlrev_b32_e32 v0, 14, v8
	v_and_b32_e32 v0, 0xffff8000, v0
	v_lshl_add_u32 v0, v9, 11, v0
	v_and_b32_e32 v1, 1, v8
	v_lshl_or_b32 v0, v1, 6, v0
	s_cselect_b64 s[6:7], -1, 0
	s_cmp_eq_u32 s10, 0
	v_lshl_add_u32 v140, v10, 1, v0
	v_lshlrev_b32_e32 v0, 14, v12
	v_bitop3_b32 v145, v15, s5, v14 bitop3:0xde
	s_cselect_b64 s[4:5], -1, 0
	v_cmp_gt_u32_e32 vcc, 2, v16
	v_and_b32_e32 v0, 0xffff8000, v0
	s_waitcnt vmcnt(6)
	s_and_b64 s[8:9], s[4:5], vcc
	v_readlane_b32 s4, v255, 33
	v_lshl_add_u32 v0, v11, 11, v0
	v_and_b32_e32 v1, 1, v12
	v_lshlrev_b32_e32 v17, 3, v16
	v_lshlrev_b32_e32 v32, 5, v16
	v_readlane_b32 s5, v255, 34
	v_lshl_or_b32 v0, v1, 6, v0
	s_mov_b32 s55, 0
	v_lshl_add_u64 v[138:139], s[4:5], 0, v[32:33]
	v_lshl_or_b32 v146, s10, 5, v17
	v_mov_b32_e32 v141, v33
	v_lshl_add_u32 v142, v13, 1, v0
	v_mov_b32_e32 v143, v33
	v_add_u32_e32 v147, 0, v18
	s_barrier
	s_branch .LBB0_207

; #define PG8_STAGE(bufoff, gbase, voff) do { _Pragma("unroll") for (int _i = 0; _i < 2; ++_i) \
;         __builtin_amdgcn_global_load_lds((const unsigned*)((const char*)(gbase) + (voff)[_i]), (LAS unsigned*)(lds + (bufoff) + ldsw + _i * 8192), 16, 0, 0); } while (0)
; #define PG8_WAIT_V(n) asm volatile("s_waitcnt vmcnt(" #n ")" ::: "memory")
; #define PG8_BAR __builtin_amdgcn_s_barrier()
; template <class Epi>
; __device__ __forceinline__ void gemm_phase(LAS unsigned char* lds, const Gemm g, const StaticOrder& S, const Epi& E) {
;     ...
;     for (int i = 0; i < 2; ++i) { int R, C; stage_rc(tid * 16 + i * 8192, R, C); const int Rb = Epi::PERM ? ((R & ~31) + perm32(R & 31)) : R;
;         voffA[i] = (unsigned)(R * g.lda + C) * 2u; voffB[i] = (unsigned)(Rb * K + C) * 2u; }
;     const size_t kstep = (size_t)(BK * 2);
;     const size_t hstepA = (size_t)HALF * g.lda * 2, hstepB = (size_t)HALF * K * 2;
;     const size_t tstepA = 2 * hstepA, tstepB = 2 * hstepB;
;     const unsigned ldsw = (unsigned)wid * 1024u;
;     const int aoff = lds_byte(wr * 64 + fr, fq * 8), boff = lds_byte(wc * 32 + fr, fq * 8);
;     ...
;     PG8_STAGE(PG8_SB(0, 0), cB, voffB); PG8_STAGE(PG8_SB(0, 1), cB + hstepB, voffB); PG8_STAGE(PG8_SA(0, 0), cA, voffA); PG8_STAGE(PG8_SA(0, 1), cA + hstepA, voffA);
;     if (wr == 1) PG8_BAR;
;     PG8_WAIT_V(2); PG8_BAR;
;     PG8_STAGE(PG8_SB(1, 0), cB + kstep, voffB); PG8_STAGE(PG8_SA(1, 0), cA + kstep, voffA); PG8_STAGE(PG8_SB(1, 1), cB + hstepB + kstep, voffB);
;     PG8_WAIT_V(6); PG8_BAR;
.LBB0_550:
	v_readlane_b32 s8, v255, 16
	v_readlane_b32 s9, v255, 17
	s_and_b64 s[8:9], s[8:9], s[0:1]
	s_and_b64 s[8:9], s[8:9], exec
	v_readlane_b32 s36, v253, 0
	v_readlane_b32 s8, v255, 27
	v_readlane_b32 s48, v253, 12
	v_readlane_b32 s49, v253, 13
	v_readlane_b32 s9, v255, 28
	s_cselect_b32 s19, s9, s49
	s_cselect_b32 s18, s8, s48
	s_and_b64 s[4:5], s[4:5], exec
	s_movk_i32 s4, 0x800
	s_cselect_b32 s7, s4, 0x2000
	s_and_b64 s[4:5], s[0:1], exec
	s_cselect_b32 s4, 0x1400, s7
	s_lshl_b32 s4, s4, 2
	v_readlane_b32 s5, v255, 13
	s_add_u32 s94, s5, s4
	v_readlane_b32 s4, v255, 15
	s_addc_u32 s95, s4, 0
	s_lshl_b32 s4, s58, 2
	s_add_u32 s96, s56, s4
	s_addc_u32 s97, s57, 0
	s_add_u32 s54, s96, 0x1000
	s_addc_u32 s55, s97, 0
	s_add_i32 m0, s88, 0x18000
	v_lshl_add_u64 v[0:1], v[0:1], 0, s[90:91]
	global_load_lds_dwordx4 v[0:1], off
	v_lshl_add_u64 v[0:1], v[2:3], 0, s[90:91]
	s_add_i32 m0, s88, 0x1a000
	s_add_i32 s75, s88, 0x8000
	global_load_lds_dwordx4 v[0:1], off
	v_lshl_add_u64 v[0:1], v[8:9], 0, s[90:91]
	s_mov_b32 m0, s75
	s_add_i32 s81, s88, 0xa000
	global_load_lds_dwordx4 v[0:1], off
	v_lshl_add_u64 v[0:1], v[10:11], 0, s[90:91]
	s_mov_b32 m0, s81
	v_cndmask_b32_e64 v138, 0.5, 1.0, s[0:1]
	global_load_lds_dwordx4 v[0:1], off
	s_add_i32 m0, s88, 0x1c000
	v_lshl_add_u64 v[0:1], v[4:5], 0, s[90:91]
	global_load_lds_dwordx4 v[0:1], off
	v_lshl_add_u64 v[0:1], v[6:7], 0, s[90:91]
	s_add_i32 m0, s88, 0x1e000
	s_and_b32 s0, s6, 3
	global_load_lds_dwordx4 v[0:1], off
	s_waitcnt vmcnt(8)
	s_barrier
	v_bfe_u32 v0, v12, 4, 2
	v_and_b32_e32 v1, 15, v12
	v_lshlrev_b32_e32 v4, 4, v0
	v_lshlrev_b32_e32 v5, 2, v1
	s_lshr_b32 s80, s59, 6
	v_lshl_or_b32 v2, s11, 6, v1
	v_lshl_or_b32 v4, v1, 6, v4
	s_lshl_b32 s1, s11, 13
	v_and_b32_e32 v1, 32, v5
	s_lshl_b32 s78, s60, 2
	v_bitop3_b32 v6, v4, s1, v1 bitop3:0xde
	s_lshl_b32 s1, s0, 12
	s_add_i32 s79, s80, -2
	s_cmpk_lt_u32 s10, 0x100
	v_bitop3_b32 v178, v4, s1, v1 bitop3:0xde
	s_cselect_b64 s[20:21], -1, 0
	s_and_b32 s1, s10, 0xffffff00
	s_lshl_b32 s4, s0, 6
	v_lshlrev_b32_e32 v3, 3, v0
	s_or_b32 s1, s4, s1
	v_and_b32_e32 v1, 63, v12
	v_lshl_or_b32 v179, s0, 5, v3
	v_cmp_eq_u32_e64 s[4:5], 0, v0
	v_or_b32_e32 v0, s1, v1
	v_readlane_b32 s22, v255, 25
	s_lshl_b32 s0, s0, 2
	v_lshlrev_b32_e32 v3, 2, v1
	s_movk_i32 s1, 0x100
	v_ashrrev_i32_e32 v1, 31, v0
	v_readlane_b32 s23, v255, 26
	s_add_i32 s72, s0, 0
	s_add_i32 s0, 0, 0x21000
	v_xor_b32_e32 v180, 64, v3
	v_xor_b32_e32 v181, 0x80, v3
	v_cmp_gt_i32_e64 s[6:7], s1, v0
	v_lshlrev_b32_e32 v3, 4, v0
	v_cmp_eq_u32_e64 s[8:9], 0, v0
	v_lshl_add_u64 v[140:141], v[0:1], 2, s[22:23]
	v_lshl_add_u32 v204, v0, 2, s0
	v_add_u32_e32 v0, v18, v16
	s_waitcnt vmcnt(6)
	s_lshl_b32 s1, s11, 8
	v_add_lshl_u32 v32, v0, v17, 1
	v_add_u32_e32 v0, v15, v13
	s_add_i32 s0, s0, s1
	v_lshl_add_u64 v[144:145], s[14:15], 0, v[32:33]
	v_add_lshl_u32 v32, v0, v14, 1
	v_add_u32_e32 v0, 0, v3
	s_mov_b32 s16, 0
	v_lshlrev_b32_e32 v190, 4, v2
	v_lshlrev_b32_e32 v191, 10, v2
	s_ashr_i32 s17, s2, 31
	s_add_i32 s72, s72, 0x20000
	v_add_u32_e32 v205, s0, v5
	v_mov_b32_e32 v142, v138
	v_mov_b32_e32 v143, v138
	v_lshl_add_u64 v[146:147], s[14:15], 0, v[32:33]
	v_add_u32_e32 v206, 0, v6
	v_add_u32_e32 v207, 0x20000, v0
	v_readlane_b32 s37, v253, 1
	v_readlane_b32 s38, v253, 2
	v_readlane_b32 s39, v253, 3
	v_readlane_b32 s40, v253, 4
	v_readlane_b32 s41, v253, 5
	v_readlane_b32 s42, v253, 6
	v_readlane_b32 s43, v253, 7
	v_readlane_b32 s44, v253, 8
	v_readlane_b32 s45, v253, 9
	v_readlane_b32 s46, v253, 10
	v_readlane_b32 s47, v253, 11
	v_readlane_b32 s50, v253, 14
	v_readlane_b32 s51, v253, 15
	s_barrier
	s_branch .LBB0_553

; #define PG8_STAGE(bufoff, gbase, voff) do { _Pragma("unroll") for (int _i = 0; _i < 2; ++_i) \
;         __builtin_amdgcn_global_load_lds((const unsigned*)((const char*)(gbase) + (voff)[_i]), (LAS unsigned*)(lds + (bufoff) + ldsw + _i * 8192), 16, 0, 0); } while (0)
; #define PG8_WAIT_V(n) asm volatile("s_waitcnt vmcnt(" #n ")" ::: "memory")
; #define PG8_BAR __builtin_amdgcn_s_barrier()
; template <class Epi>
; __device__ __forceinline__ void gemm_phase(LAS unsigned char* lds, const Gemm g, const StaticOrder& S, const Epi& E) {
;     ...
;     for (int i = 0; i < 2; ++i) { int R, C; stage_rc(tid * 16 + i * 8192, R, C); const int Rb = Epi::PERM ? ((R & ~31) + perm32(R & 31)) : R;
;         voffA[i] = (unsigned)(R * g.lda + C) * 2u; voffB[i] = (unsigned)(Rb * K + C) * 2u; }
;     const size_t kstep = (size_t)(BK * 2);
;     const size_t hstepA = (size_t)HALF * g.lda * 2, hstepB = (size_t)HALF * K * 2;
;     const size_t tstepA = 2 * hstepA, tstepB = 2 * hstepB;
;     const unsigned ldsw = (unsigned)wid * 1024u;
;     const int aoff = lds_byte(wr * 64 + fr, fq * 8), boff = lds_byte(wc * 32 + fr, fq * 8);
;     ...
;     PG8_STAGE(PG8_SB(0, 0), cB, voffB); PG8_STAGE(PG8_SB(0, 1), cB + hstepB, voffB); PG8_STAGE(PG8_SA(0, 0), cA, voffA); PG8_STAGE(PG8_SA(0, 1), cA + hstepA, voffA);
;     if (wr == 1) PG8_BAR;
;     PG8_WAIT_V(2); PG8_BAR;
;     PG8_STAGE(PG8_SB(1, 0), cB + kstep, voffB); PG8_STAGE(PG8_SA(1, 0), cA + kstep, voffA); PG8_STAGE(PG8_SB(1, 1), cB + hstepB + kstep, voffB);
;     PG8_WAIT_V(6); PG8_BAR;
.LBB0_617:
	v_readlane_b32 s4, v255, 13
	s_add_u32 s72, s4, 0x2000
	v_readlane_b32 s4, v255, 15
	s_addc_u32 s73, s4, 0
	s_lshl_b32 s4, s58, 2
	s_add_u32 s75, s56, s4
	s_addc_u32 s78, s57, 0
	s_add_u32 s79, s75, 0x1000
	s_addc_u32 s80, s78, 0
	s_add_i32 m0, s54, 0x18000
	v_lshl_add_u64 v[0:1], v[0:1], 0, s[90:91]
	global_load_lds_dwordx4 v[0:1], off
	v_lshl_add_u64 v[0:1], v[2:3], 0, s[90:91]
	s_add_i32 m0, s54, 0x1a000
	s_add_i32 s89, s54, 0x8000
	global_load_lds_dwordx4 v[0:1], off
	v_lshl_add_u64 v[0:1], v[8:9], 0, s[90:91]
	s_mov_b32 m0, s89
	s_add_i32 s92, s54, 0xa000
	global_load_lds_dwordx4 v[0:1], off
	v_lshl_add_u64 v[0:1], v[10:11], 0, s[90:91]
	s_mov_b32 m0, s92
	v_bfe_u32 v19, v12, 4, 2
	global_load_lds_dwordx4 v[0:1], off
	s_add_i32 m0, s54, 0x1c000
	v_lshl_add_u64 v[0:1], v[4:5], 0, s[90:91]
	global_load_lds_dwordx4 v[0:1], off
	v_lshl_add_u64 v[0:1], v[6:7], 0, s[90:91]
	s_add_i32 m0, s54, 0x1e000
	v_and_b32_e32 v20, 15, v12
	global_load_lds_dwordx4 v[0:1], off
	s_waitcnt vmcnt(8)
	s_barrier
	v_lshlrev_b32_e32 v23, 4, v19
	v_lshl_or_b32 v21, s0, 6, v20
	v_lshl_or_b32 v23, v20, 6, v23
	v_lshlrev_b32_e32 v20, 2, v20
	s_and_b32 s1, s1, 3
	s_lshr_b32 s88, s59, 6
	s_lshl_b32 s4, s0, 13
	v_and_b32_e32 v24, 32, v20
	s_lshl_b32 s81, s60, 2
	v_bitop3_b32 v25, v23, s4, v24 bitop3:0xde
	s_lshl_b32 s4, s1, 12
	s_add_i32 s76, s88, -2
	s_cmpk_lt_u32 s6, 0x100
	v_bitop3_b32 v174, v23, s4, v24 bitop3:0xde
	s_cselect_b64 s[18:19], -1, 0
	s_and_b32 s4, s6, 0xffffff00
	s_lshl_b32 s5, s1, 6
	v_lshlrev_b32_e32 v22, 3, v19
	s_or_b32 s6, s5, s4
	v_and_b32_e32 v0, 63, v12
	v_lshl_or_b32 v175, s1, 5, v22
	v_lshlrev_b32_e32 v1, 2, v0
	v_or_b32_e32 v0, s6, v0
	v_readlane_b32 s10, v255, 25
	s_lshl_b32 s1, s1, 2
	v_xor_b32_e32 v176, 64, v1
	v_xor_b32_e32 v177, 0x80, v1
	s_movk_i32 s6, 0x100
	v_ashrrev_i32_e32 v1, 31, v0
	v_readlane_b32 s11, v255, 26
	s_add_i32 s95, s1, 0
	s_add_i32 s1, 0, 0x21000
	v_cmp_gt_i32_e64 s[6:7], s6, v0
	v_lshlrev_b32_e32 v2, 4, v0
	v_cmp_eq_u32_e64 s[8:9], 0, v0
	v_lshl_add_u64 v[138:139], v[0:1], 2, s[10:11]
	v_lshl_add_u32 v180, v0, 2, s1
	v_add_u32_e32 v0, v18, v16
	s_waitcnt vmcnt(6)
	s_lshl_b32 s0, s0, 8
	v_add_lshl_u32 v32, v0, v17, 1
	v_add_u32_e32 v0, v15, v13
	s_add_i32 s1, s1, s0
	v_lshl_add_u64 v[140:141], s[14:15], 0, v[32:33]
	v_add_lshl_u32 v32, v0, v14, 1
	v_add_u32_e32 v0, 0, v2
	s_mov_b32 s93, 0
	v_cmp_eq_u32_e64 s[4:5], 0, v19
	v_lshlrev_b32_e32 v178, 4, v21
	v_lshlrev_b32_e32 v179, 10, v21
	s_ashr_i32 s94, s2, 31
	s_add_i32 s95, s95, 0x20000
	v_add_u32_e32 v181, s1, v20
	v_lshl_add_u64 v[142:143], s[14:15], 0, v[32:33]
	v_add_u32_e32 v190, 0, v25
	v_add_u32_e32 v191, 0x20000, v0
	s_barrier
	s_branch .LBB0_620

; #define PG8_STAGE(bufoff, gbase, voff) do { _Pragma("unroll") for (int _i = 0; _i < 2; ++_i) \
;         __builtin_amdgcn_global_load_lds((const unsigned*)((const char*)(gbase) + (voff)[_i]), (LAS unsigned*)(lds + (bufoff) + ldsw + _i * 8192), 16, 0, 0); } while (0)
; #define PG8_WAIT_V(n) asm volatile("s_waitcnt vmcnt(" #n ")" ::: "memory")
; #define PG8_BAR __builtin_amdgcn_s_barrier()
; template <class Epi>
; __device__ __forceinline__ void gemm_phase(LAS unsigned char* lds, const Gemm g, const StaticOrder& S, const Epi& E) {
;     ...
;     for (int i = 0; i < 2; ++i) { int R, C; stage_rc(tid * 16 + i * 8192, R, C); const int Rb = Epi::PERM ? ((R & ~31) + perm32(R & 31)) : R;
;         voffA[i] = (unsigned)(R * g.lda + C) * 2u; voffB[i] = (unsigned)(Rb * K + C) * 2u; }
;     const size_t kstep = (size_t)(BK * 2);
;     const size_t hstepA = (size_t)HALF * g.lda * 2, hstepB = (size_t)HALF * K * 2;
;     const size_t tstepA = 2 * hstepA, tstepB = 2 * hstepB;
;     const unsigned ldsw = (unsigned)wid * 1024u;
;     const int aoff = lds_byte(wr * 64 + fr, fq * 8), boff = lds_byte(wc * 32 + fr, fq * 8);
;     ...
;     PG8_STAGE(PG8_SB(0, 0), cB, voffB); PG8_STAGE(PG8_SB(0, 1), cB + hstepB, voffB); PG8_STAGE(PG8_SA(0, 0), cA, voffA); PG8_STAGE(PG8_SA(0, 1), cA + hstepA, voffA);
;     if (wr == 1) PG8_BAR;
;     PG8_WAIT_V(2); PG8_BAR;
;     PG8_STAGE(PG8_SB(1, 0), cB + kstep, voffB); PG8_STAGE(PG8_SA(1, 0), cA + kstep, voffA); PG8_STAGE(PG8_SB(1, 1), cB + hstepB + kstep, voffB);
;     PG8_WAIT_V(6); PG8_BAR;
.LBB0_685:
	v_bfe_u32 v17, v8, 4, 2
	v_readlane_b32 s4, v255, 13
	v_and_b32_e32 v18, 15, v8
	v_lshlrev_b32_e32 v21, 4, v17
	s_add_u32 s35, s4, 0x8000
	v_readlane_b32 s4, v255, 15
	v_lshl_or_b32 v19, s0, 6, v18
	v_lshl_or_b32 v21, v18, 6, v21
	v_lshlrev_b32_e32 v18, 2, v18
	s_addc_u32 s54, s4, 0
	s_and_b32 s1, s1, 3
	s_lshl_b32 s4, s0, 13
	v_and_b32_e32 v22, 32, v18
	s_add_i32 m0, s28, 0x18000
	v_lshl_add_u64 v[6:7], v[6:7], 0, s[90:91]
	v_bitop3_b32 v23, v21, s4, v22 bitop3:0xde
	s_lshl_b32 s4, s1, 12
	global_load_lds_dwordx4 v[6:7], off
	v_lshl_add_u64 v[4:5], v[4:5], 0, s[90:91]
	s_add_i32 m0, s28, 0x1a000
	s_add_i32 s55, s28, 0x8000
	s_add_i32 s68, s28, 0xa000
	v_bitop3_b32 v172, v21, s4, v22 bitop3:0xde
	global_load_lds_dwordx4 v[4:5], off
	v_lshl_add_u64 v[0:1], v[0:1], 0, s[90:91]
	s_mov_b32 m0, s55
	s_add_u32 s4, s20, 0xb0080
	global_load_lds_dwordx4 v[0:1], off
	v_lshl_add_u64 v[0:1], v[2:3], 0, s[90:91]
	s_mov_b32 m0, s68
	s_addc_u32 s5, s21, 0
	global_load_lds_dwordx4 v[0:1], off
	s_add_i32 m0, s28, 0x1c000
	v_lshl_add_u64 v[0:1], s[4:5], 0, v[132:133]
	global_load_lds_dwordx4 v[0:1], off
	v_lshl_add_u64 v[0:1], s[4:5], 0, v[136:137]
	s_add_i32 m0, s28, 0x1e000
	s_cmpk_lt_u32 s6, 0x100
	global_load_lds_dwordx4 v[0:1], off
	s_waitcnt vmcnt(8)
	s_barrier
	s_cselect_b64 s[14:15], -1, 0
	s_and_b32 s4, s6, 0xffffff00
	s_lshl_b32 s5, s1, 6
	v_lshlrev_b32_e32 v20, 3, v17
	s_or_b32 s6, s5, s4
	v_and_b32_e32 v0, 63, v8
	v_lshl_or_b32 v173, s1, 5, v20
	v_lshlrev_b32_e32 v1, 2, v0
	v_or_b32_e32 v0, s6, v0
	v_readlane_b32 s10, v255, 25
	s_lshl_b32 s1, s1, 2
	v_xor_b32_e32 v174, 64, v1
	v_xor_b32_e32 v175, 0x80, v1
	v_ashrrev_i32_e32 v1, 31, v0
	v_readlane_b32 s11, v255, 26
	s_add_i32 s1, s1, 0
	s_movk_i32 s6, 0x100
	v_lshl_add_u64 v[138:139], v[0:1], 2, s[10:11]
	s_add_i32 s10, s1, 0x20000
	s_add_i32 s1, 0, 0x21000
	s_lshl_b32 s0, s0, 8
	s_movk_i32 s22, 0xb00
	v_cmp_gt_i32_e64 s[6:7], s6, v0
	v_lshlrev_b32_e32 v3, 4, v0
	v_cmp_eq_u32_e64 s[8:9], 0, v0
	v_lshl_add_u32 v177, v0, 2, s1
	s_add_i32 s1, s1, s0
	v_lshrrev_b32_e32 v1, 1, v13
	v_mul_lo_u32 v0, v15, s22
	s_mov_b32 s11, 0xb000
	v_add_u32_e32 v178, s1, v18
	v_mad_u64_u32 v[0:1], s[0:1], v1, s11, v[0:1]
	v_or_b32_e32 v0, v0, v14
	v_add_lshl_u32 v32, v0, v16, 1
	v_lshrrev_b32_e32 v1, 1, v9
	v_mul_lo_u32 v0, v11, s22
	v_mad_u64_u32 v[0:1], s[0:1], v1, s11, v[0:1]
	s_waitcnt vmcnt(6)
	s_mov_b64 s[16:17], 0xb0080
	v_or_b32_e32 v0, v0, v10
	v_lshlrev_b32_e32 v2, 4, v19
	v_lshl_add_u64 v[140:141], v[32:33], 0, s[16:17]
	v_add_lshl_u32 v32, v0, v12, 1
	v_add_u32_e32 v0, 0, v3
	s_mov_b32 s69, 0
	v_cmp_eq_u32_e64 s[4:5], 0, v17
	v_lshlrev_b32_e32 v176, 10, v19
	s_ashr_i32 s70, s2, 31
	v_lshl_add_u64 v[142:143], v[32:33], 0, s[16:17]
	v_add_u32_e32 v179, 0, v23
	v_add_u32_e32 v180, 0x20000, v0
	v_add_u32_e32 v181, s10, v2
	s_barrier
	s_branch .LBB0_688

; #define PG8_STAGE(bufoff, gbase, voff) do { _Pragma("unroll") for (int _i = 0; _i < 2; ++_i) \
;         __builtin_amdgcn_global_load_lds((const unsigned*)((const char*)(gbase) + (voff)[_i]), (LAS unsigned*)(lds + (bufoff) + ldsw + _i * 8192), 16, 0, 0); } while (0)
; #define PG8_WAIT_V(n) asm volatile("s_waitcnt vmcnt(" #n ")" ::: "memory")
; #define PG8_BAR __builtin_amdgcn_s_barrier()
; template <class Epi>
; __device__ __forceinline__ void gemm_phase(LAS unsigned char* lds, const Gemm g, const StaticOrder& S, const Epi& E) {
;     ...
;     for (int i = 0; i < 2; ++i) { int R, C; stage_rc(tid * 16 + i * 8192, R, C); const int Rb = Epi::PERM ? ((R & ~31) + perm32(R & 31)) : R;
;         voffA[i] = (unsigned)(R * g.lda + C) * 2u; voffB[i] = (unsigned)(Rb * K + C) * 2u; }
;     const size_t kstep = (size_t)(BK * 2);
;     const size_t hstepA = (size_t)HALF * g.lda * 2, hstepB = (size_t)HALF * K * 2;
;     const size_t tstepA = 2 * hstepA, tstepB = 2 * hstepB;
;     const unsigned ldsw = (unsigned)wid * 1024u;
;     const int aoff = lds_byte(wr * 64 + fr, fq * 8), boff = lds_byte(wc * 32 + fr, fq * 8);
;     ...
;     PG8_STAGE(PG8_SB(0, 0), cB, voffB); PG8_STAGE(PG8_SB(0, 1), cB + hstepB, voffB); PG8_STAGE(PG8_SA(0, 0), cA, voffA); PG8_STAGE(PG8_SA(0, 1), cA + hstepA, voffA);
;     if (wr == 1) PG8_BAR;
;     PG8_WAIT_V(2); PG8_BAR;
;     PG8_STAGE(PG8_SB(1, 0), cB + kstep, voffB); PG8_STAGE(PG8_SA(1, 0), cA + kstep, voffA); PG8_STAGE(PG8_SB(1, 1), cB + hstepB + kstep, voffB);
;     PG8_WAIT_V(6); PG8_BAR;
.LBB0_747:
	s_lshl_b32 s7, s7, 5
	s_and_b32 s11, s7, 0x60
	s_add_i32 m0, s28, 0x18000
	v_lshl_add_u64 v[6:7], v[6:7], 0, s[90:91]
	s_lshl_b32 s10, s6, 13
	s_lshl_b32 s7, s11, 7
	global_load_lds_dwordx4 v[6:7], off
	v_lshl_add_u64 v[4:5], v[4:5], 0, s[90:91]
	s_add_i32 m0, s28, 0x1a000
	s_add_i32 s35, s28, 0x8000
	s_add_i32 s54, s28, 0xa000
	global_load_lds_dwordx4 v[4:5], off
	v_lshl_add_u64 v[0:1], v[0:1], 0, s[90:91]
	s_mov_b32 m0, s35
	s_add_u32 s8, s18, 0x40080
	global_load_lds_dwordx4 v[0:1], off
	v_lshl_add_u64 v[0:1], v[2:3], 0, s[90:91]
	s_mov_b32 m0, s54
	s_addc_u32 s9, s19, 0
	global_load_lds_dwordx4 v[0:1], off
	s_add_i32 m0, s28, 0x1c000
	v_lshl_add_u64 v[0:1], s[8:9], 0, v[134:135]
	global_load_lds_dwordx4 v[0:1], off
	v_lshl_add_u64 v[0:1], s[8:9], 0, v[130:131]
	s_add_i32 m0, s28, 0x1e000
	s_cmpk_lt_u32 s5, 0x100
	global_load_lds_dwordx4 v[0:1], off
	s_waitcnt vmcnt(8)
	s_barrier
	v_lshrrev_b32_e32 v1, 1, v8
	v_and_b32_e32 v1, 24, v1
	v_and_b32_e32 v0, 15, v8
	v_lshlrev_b32_e32 v2, 1, v1
	v_lshl_or_b32 v142, s6, 6, v0
	v_lshl_or_b32 v0, v0, 6, v2
	v_lshlrev_b32_e32 v2, 2, v8
	v_and_b32_e32 v2, 32, v2
	v_bitop3_b32 v3, v0, s10, v2 bitop3:0xde
	v_bitop3_b32 v143, v0, s7, v2 bitop3:0xde
	v_lshlrev_b32_e32 v0, 14, v9
	v_and_b32_e32 v0, 0xffff8000, v0
	v_or_b32_e32 v144, s11, v1
	v_lshl_add_u32 v0, v10, 11, v0
	v_and_b32_e32 v1, 1, v9
	v_lshl_or_b32 v0, v1, 6, v0
	v_lshl_add_u32 v138, v11, 1, v0
	v_lshlrev_b32_e32 v0, 14, v13
	v_and_b32_e32 v0, 0xffff8000, v0
	s_waitcnt vmcnt(6)
	v_lshl_add_u32 v0, v12, 11, v0
	v_and_b32_e32 v1, 1, v13
	v_lshl_or_b32 v0, v1, 6, v0
	s_sext_i32_i16 s17, s4
	s_cselect_b64 s[6:7], -1, 0
	v_mov_b32_e32 v139, v33
	v_lshl_add_u32 v140, v14, 1, v0
	v_mov_b32_e32 v141, v33
	s_mov_b32 s55, 0
	v_add_u32_e32 v145, 0, v3
	s_barrier
	s_branch .LBB0_750

; #define PG8_STAGE(bufoff, gbase, voff) do { _Pragma("unroll") for (int _i = 0; _i < 2; ++_i) \
;         __builtin_amdgcn_global_load_lds((const unsigned*)((const char*)(gbase) + (voff)[_i]), (LAS unsigned*)(lds + (bufoff) + ldsw + _i * 8192), 16, 0, 0); } while (0)
; #define PG8_WAIT_V(n) asm volatile("s_waitcnt vmcnt(" #n ")" ::: "memory")
; #define PG8_BAR __builtin_amdgcn_s_barrier()
; template <class Epi>
; __device__ __forceinline__ void gemm_phase(LAS unsigned char* lds, const Gemm g, const StaticOrder& S, const Epi& E) {
;     ...
;     for (int i = 0; i < 2; ++i) { int R, C; stage_rc(tid * 16 + i * 8192, R, C); const int Rb = Epi::PERM ? ((R & ~31) + perm32(R & 31)) : R;
;         voffA[i] = (unsigned)(R * g.lda + C) * 2u; voffB[i] = (unsigned)(Rb * K + C) * 2u; }
;     const size_t kstep = (size_t)(BK * 2);
;     const size_t hstepA = (size_t)HALF * g.lda * 2, hstepB = (size_t)HALF * K * 2;
;     const size_t tstepA = 2 * hstepA, tstepB = 2 * hstepB;
;     const unsigned ldsw = (unsigned)wid * 1024u;
;     const int aoff = lds_byte(wr * 64 + fr, fq * 8), boff = lds_byte(wc * 32 + fr, fq * 8);
;     ...
;     PG8_STAGE(PG8_SB(0, 0), cB, voffB); PG8_STAGE(PG8_SB(0, 1), cB + hstepB, voffB); PG8_STAGE(PG8_SA(0, 0), cA, voffA); PG8_STAGE(PG8_SA(0, 1), cA + hstepA, voffA);
;     if (wr == 1) PG8_BAR;
;     PG8_WAIT_V(2); PG8_BAR;
;     PG8_STAGE(PG8_SB(1, 0), cB + kstep, voffB); PG8_STAGE(PG8_SA(1, 0), cA + kstep, voffA); PG8_STAGE(PG8_SB(1, 1), cB + hstepB + kstep, voffB);
;     PG8_WAIT_V(6); PG8_BAR;
.LBB0_910:
	s_sext_i32_i16 s93, s8
	s_or_b64 s[8:9], s[10:11], s[6:7]
	v_readlane_b32 s0, v255, 22
	s_and_b64 s[8:9], s[8:9], exec
	v_readlane_b32 s1, v255, 23
	s_cselect_b32 s9, s87, s1
	s_cselect_b32 s8, s86, s0
	s_and_b64 s[16:17], s[10:11], exec
	s_cselect_b32 s78, 0x900, s14
	s_and_b64 s[16:17], s[6:7], exec
	v_bfe_u32 v15, v14, 4, 2
	s_cselect_b32 s14, 16, 4
	s_and_b64 s[10:11], s[10:11], exec
	v_and_b32_e32 v146, 15, v14
	v_lshlrev_b32_e32 v17, 4, v15
	v_lshlrev_b32_e32 v14, 2, v14
	s_cselect_b32 s79, 9, s14
	s_and_b32 s16, s15, 3
	v_lshl_or_b32 v17, v146, 6, v17
	s_lshl_b32 s10, s13, 13
	v_and_b32_e32 v14, 32, v14
	s_add_i32 m0, s73, 0x18000
	v_lshl_add_u64 v[6:7], v[6:7], 0, s[90:91]
	s_lshl_b32 s80, s13, 6
	v_bitop3_b32 v18, v17, s10, v14 bitop3:0xde
	s_lshl_b32 s10, s16, 12
	global_load_lds_dwordx4 v[6:7], off
	v_lshl_add_u64 v[4:5], v[4:5], 0, s[90:91]
	s_add_i32 m0, s73, 0x1a000
	s_add_i32 s81, s73, 0x8000
	s_add_i32 s88, s73, 0xa000
	v_bitop3_b32 v147, v17, s10, v14 bitop3:0xde
	global_load_lds_dwordx4 v[4:5], off
	v_lshl_add_u64 v[0:1], v[0:1], 0, s[90:91]
	s_mov_b32 m0, s81
	s_add_u32 s10, s28, 0x40080
	global_load_lds_dwordx4 v[0:1], off
	v_lshl_add_u64 v[0:1], v[2:3], 0, s[90:91]
	s_mov_b32 m0, s88
	s_addc_u32 s11, s29, 0
	global_load_lds_dwordx4 v[0:1], off
	s_add_i32 m0, s73, 0x1c000
	v_lshl_add_u64 v[0:1], s[10:11], 0, v[134:135]
	global_load_lds_dwordx4 v[0:1], off
	v_lshl_add_u64 v[0:1], s[10:11], 0, v[130:131]
	s_add_i32 m0, s73, 0x1e000
	s_cmpk_lt_u32 s12, 0x100
	global_load_lds_dwordx4 v[0:1], off
	s_waitcnt vmcnt(8)
	s_barrier
	v_lshlrev_b32_e32 v0, 14, v8
	v_and_b32_e32 v0, 0xffff8000, v0
	v_lshl_add_u32 v0, v9, 11, v0
	v_and_b32_e32 v1, 1, v8
	v_lshl_or_b32 v0, v1, 6, v0
	v_lshl_add_u32 v140, v10, 1, v0
	v_lshlrev_b32_e32 v0, 14, v12
	s_cselect_b64 s[10:11], -1, 0
	s_cmp_eq_u32 s16, 0
	v_and_b32_e32 v0, 0xffff8000, v0
	s_waitcnt vmcnt(6)
	s_cselect_b64 s[12:13], -1, 0
	v_cmp_gt_u32_e32 vcc, 2, v15
	v_readlane_b32 s0, v255, 33
	v_lshl_add_u32 v0, v11, 11, v0
	v_and_b32_e32 v1, 1, v12
	v_lshlrev_b32_e32 v16, 3, v15
	s_and_b64 s[12:13], s[12:13], vcc
	v_subrev_co_u32_e32 v148, vcc, 13, v146
	v_lshlrev_b32_e32 v32, 5, v15
	v_readlane_b32 s1, v255, 34
	s_xor_b64 s[6:7], s[6:7], -1
	v_lshl_or_b32 v0, v1, 6, v0
	s_mov_b32 s89, 0
	v_lshl_add_u64 v[138:139], s[0:1], 0, v[32:33]
	s_or_b64 s[14:15], s[6:7], vcc
	v_lshl_or_b32 v149, s16, 5, v16
	s_lshl_b32 s92, s78, 4
	v_mov_b32_e32 v141, v33
	v_lshl_add_u32 v142, v13, 1, v0
	v_mov_b32_e32 v143, v33
	v_add_u32_e32 v150, 0, v18
	s_barrier
	s_branch .LBB0_913
